# v27 + SwiGLU rs LDS preload + conv double-buffer + StaticOrder::next() divide-by-8 as shift in the three 128-panel unit heads
# speedup vs baseline: 1.0049x; 1.0049x over previous
;     __host__ __device__ bool next(int i, Unit& u) const {
;     ...
;         int wgid = (int)L; { const int q = nwg / NXCD, r = nwg % NXCD, xcd = wgid % NXCD, off = wgid / NXCD; wgid = (xcd < r ? xcd * (q + 1) : r * (q + 1) + (xcd - r) * q) + off; }
;         const int nig = WGM * nN, gid = wgid / nig, fm = gid * WGM, gsz = (nM - fm) < WGM ? (nM - fm) : WGM;
;         u.pm = fm + ((wgid % nig) % gsz); u.pn = (wgid % nig) / gsz; u.kind = 0; return true;
.LBB0_139:
	s_add_i32 s47, s47, 1
	s_mul_i32 s4, s47, s95
	s_mul_hi_u32 s5, s47, s94
	s_add_i32 s5, s5, s4
	s_mul_i32 s4, s47, s94
	s_add_u32 s26, s4, s88
	s_addc_u32 s27, s5, s89
	v_mov_b64_e32 v[2:3], 0xb00
	v_cmp_gt_i64_e32 vcc, s[26:27], v[200:201]
	v_cmp_lt_i64_e64 s[4:5], s[26:27], v[2:3]
	s_cbranch_vccnz .LBB0_141
	s_ashr_i32 s20, s26, 31
	s_lshr_b32 s20, s20, 29
	s_add_i32 s20, s26, s20
	s_ashr_i32 s21, s20, 3
	s_and_b32 s20, s20, -8
	s_sub_i32 s20, s26, s20
	s_cmp_lt_i32 s20, 0
	s_cselect_b32 s22, s53, 0x160
	s_mul_i32 s20, s20, s22
	s_add_i32 s20, s20, s21
	s_mul_hi_i32 s21, s20, 0x2e8ba2e9
	s_lshr_b32 s22, s21, 31
	s_ashr_i32 s21, s21, 5
	s_add_i32 s21, s21, s22
	s_lshl_b32 s22, s21, 3
	s_mulk_i32 s21, 0xb0
	s_sub_i32 s21, s20, s21
	s_lshr_b32 s20, s21, 3
	s_and_b32 s21, s21, 7
	s_add_i32 s22, s22, s21

;     __host__ __device__ bool next(int i, Unit& u) const {
;     ...
;         int wgid = (int)L; { const int q = nwg / NXCD, r = nwg % NXCD, xcd = wgid % NXCD, off = wgid / NXCD; wgid = (xcd < r ? xcd * (q + 1) : r * (q + 1) + (xcd - r) * q) + off; }
;         const int nig = WGM * nN, gid = wgid / nig, fm = gid * WGM, gsz = (nM - fm) < WGM ? (nM - fm) : WGM;
;         u.pm = fm + ((wgid % nig) % gsz); u.pn = (wgid % nig) / gsz; u.kind = 0; return true;
.LBB0_544:
	s_add_i32 s81, s81, 1
	s_mul_i32 s12, s81, s95
	s_mul_hi_u32 s13, s81, s94
	s_add_i32 s13, s13, s12
	s_mul_i32 s12, s81, s94
	s_add_u32 s16, s12, s88
	s_addc_u32 s17, s13, s89
	v_mov_b64_e32 v[2:3], 0x580
	v_cmp_lt_i64_e64 s[44:45], s[16:17], v[2:3]
	v_mov_b64_e32 v[2:3], 0x57f
	v_cmp_gt_i64_e32 vcc, s[16:17], v[2:3]
	s_cbranch_vccnz .LBB0_546
	s_ashr_i32 s12, s16, 31
	s_lshr_b32 s12, s12, 29
	s_add_i32 s12, s16, s12
	s_ashr_i32 s13, s12, 3
	s_and_b32 s12, s12, -8
	s_sub_i32 s12, s16, s12
	s_cmp_lt_i32 s12, 0
	s_movk_i32 s14, 0xb1
	s_cselect_b32 s14, s14, 0xb0
	s_mul_i32 s12, s12, s14
	s_add_i32 s12, s12, s13
	s_mul_hi_i32 s13, s12, 0x2e8ba2e9
	s_lshr_b32 s14, s13, 31
	s_ashr_i32 s13, s13, 4
	s_add_i32 s13, s13, s14
	s_lshl_b32 s14, s13, 3
	s_mulk_i32 s13, 0x58
	s_sub_i32 s12, s12, s13
	s_lshr_b32 s50, s12, 3
	s_and_b32 s12, s12, 7
	s_add_i32 s52, s14, s12

;     __host__ __device__ bool next(int i, Unit& u) const {
;     ...
;         int wgid = (int)L; { const int q = nwg / NXCD, r = nwg % NXCD, xcd = wgid % NXCD, off = wgid / NXCD; wgid = (xcd < r ? xcd * (q + 1) : r * (q + 1) + (xcd - r) * q) + off; }
;         const int nig = WGM * nN, gid = wgid / nig, fm = gid * WGM, gsz = (nM - fm) < WGM ? (nM - fm) : WGM;
;         u.pm = fm + ((wgid % nig) % gsz); u.pn = (wgid % nig) / gsz; u.kind = 0; return true;
.LBB0_1093:
	s_ashr_i32 s6, s38, 3
	s_add_i32 s6, s40, s6
	s_ashr_i32 s7, s6, 31
	s_lshr_b32 s7, s7, 27
	s_add_i32 s7, s6, s7
	s_ashr_i32 s38, s7, 5
	s_lshl_b32 s38, s38, 3
	s_andn2_b32 s7, s7, 31
	s_sub_i32 s6, s6, s7
	s_lshr_b32 s58, s6, 3
	s_and_b32 s6, s6, 7
	s_add_i32 s59, s38, s6
	v_readlane_b32 s38, v254, 48
	v_readlane_b32 s39, v254, 49
